# v24
# baseline (speedup 1.0000x reference)
.Lp7_procb:
	v_mul_f32_e32 v124, v108, v108
	v_mul_f32_e32 v125, v104, v104
	v_mul_f32_e32 v126, v116, v116
	v_mul_f32_e32 v127, v112, v112
	v_fmac_f32_e32 v124, v109, v109
	v_fmac_f32_e32 v125, v105, v105
	v_fmac_f32_e32 v126, v117, v117
	v_fmac_f32_e32 v127, v113, v113
	v_fmac_f32_e32 v124, v110, v110
	v_fmac_f32_e32 v125, v106, v106
	v_fmac_f32_e32 v126, v118, v118
	v_fmac_f32_e32 v127, v114, v114
	v_fmac_f32_e32 v124, v111, v111
	v_fmac_f32_e32 v125, v107, v107
	v_fmac_f32_e32 v126, v119, v119
	v_fmac_f32_e32 v127, v115, v115
	v_add_f32_e32 v128, v124, v125
	v_add_f32_e32 v128, v127, v128
	v_add_f32_e32 v128, v126, v128
	ds_bpermute_b32 v129, v1, v128
	s_waitcnt lgkmcnt(0)
	v_add_f32_e32 v128, v128, v129
	ds_bpermute_b32 v129, v40, v128
	s_waitcnt lgkmcnt(0)
	v_add_f32_e32 v128, v128, v129
	ds_bpermute_b32 v129, v41, v128
	s_waitcnt lgkmcnt(0)
	v_add_f32_e32 v128, v128, v129
	ds_bpermute_b32 v129, v42, v128
	s_waitcnt lgkmcnt(0)
	v_add_f32_e32 v128, v128, v129
	ds_bpermute_b32 v129, v43, v128
	s_waitcnt lgkmcnt(0)
	v_add_f32_e32 v128, v128, v129
	ds_bpermute_b32 v129, v44, v128
	s_waitcnt lgkmcnt(0)
	v_add_f32_e32 v128, v128, v129
	v_fmamk_f32 v128, v128, 0x3a800000, v211
	v_cmp_gt_f32_e32 vcc, s26, v128
	v_mul_f32_e32 v129, 0x4b800000, v128
	s_nop 0
	v_cndmask_b32_e32 v128, v128, v129, vcc
	v_rsq_f32_e32 v128, v128
	s_nop 0
	v_mul_f32_e32 v129, 0x45800000, v128
	v_cndmask_b32_e32 v140, v128, v129, vcc
	s_nop 0
	v_pk_mul_f32 v[142:143], v[72:73], v[140:141] op_sel_hi:[1,0]
	v_pk_mul_f32 v[144:145], v[74:75], v[140:141] op_sel_hi:[1,0]
	v_pk_mul_f32 v[146:147], v[76:77], v[140:141] op_sel_hi:[1,0]
	v_pk_mul_f32 v[148:149], v[78:79], v[140:141] op_sel_hi:[1,0]
	v_pk_mul_f32 v[150:151], v[80:81], v[140:141] op_sel_hi:[1,0]
	v_pk_mul_f32 v[152:153], v[82:83], v[140:141] op_sel_hi:[1,0]
	v_pk_mul_f32 v[154:155], v[84:85], v[140:141] op_sel_hi:[1,0]
	v_pk_mul_f32 v[156:157], v[86:87], v[140:141] op_sel_hi:[1,0]
	v_pk_mul_f32 v[104:105], v[104:105], v[142:143]
	v_pk_mul_f32 v[106:107], v[106:107], v[144:145]
	v_pk_mul_f32 v[108:109], v[108:109], v[146:147]
	v_pk_mul_f32 v[110:111], v[110:111], v[148:149]
	v_pk_mul_f32 v[112:113], v[112:113], v[150:151]
	v_pk_mul_f32 v[114:115], v[114:115], v[152:153]
	v_pk_mul_f32 v[116:117], v[116:117], v[154:155]
	v_pk_mul_f32 v[118:119], v[118:119], v[156:157]
	global_store_dwordx4 v[122:123], v[104:107], off
	global_store_dwordx4 v[122:123], v[108:111], off offset:1024
	global_store_dwordx4 v[122:123], v[112:115], off offset:2048
	global_store_dwordx4 v[122:123], v[116:119], off offset:3072
	s_sub_u32 s16, s16, 1
	s_cmp_lg_u32 s16, 0
	s_cbranch_scc1 .Lp7_loop
	v_add_u32_e32 v18, 0x10000, v18
	s_load_dwordx2 s[12:13], s[0:1], 0xc8
	v_ashrrev_i32_e32 v19, 31, v18
	v_lshlrev_b64 v[120:121], 12, v[18:19]
	v_lshl_add_u64 v[120:121], v[22:23], 0, v[120:121]
	global_load_dwordx4 v[88:91], v[120:121], off
	global_load_dwordx4 v[92:95], v[120:121], off offset:1024
	global_load_dwordx4 v[96:99], v[120:121], off offset:2048
	global_load_dwordx4 v[100:103], v[120:121], off offset:3072
	v_add_u32_e32 v124, 0xffff0000, v18
	v_mov_b32_e32 v125, v0
	v_lshlrev_b64 v[124:125], 12, v[124:125]
	v_mov_b32_e32 v126, v24
	v_mov_b32_e32 v127, v0
	s_waitcnt lgkmcnt(0)
	s_add_u32 s12, s12, 0x2b27800
	s_addc_u32 s13, s13, 0
	v_lshl_add_u64 v[122:123], s[12:13], 0, v[124:125]
	v_lshl_add_u64 v[122:123], v[122:123], 0, v[126:127]
	s_mov_b64 s[20:21], 0x800000
	global_load_dwordx4 v[104:107], v[122:123], off
	global_load_dwordx4 v[108:111], v[122:123], off offset:1024
	global_load_dwordx4 v[112:115], v[122:123], off offset:2048
	global_load_dwordx4 v[116:119], v[122:123], off offset:3072
	v_lshl_add_u64 v[122:123], v[122:123], 0, s[20:21]
	global_load_dwordx4 v[160:163], v[122:123], off
	global_load_dwordx4 v[164:167], v[122:123], off offset:1024
	global_load_dwordx4 v[168:171], v[122:123], off offset:2048
	global_load_dwordx4 v[172:175], v[122:123], off offset:3072
	v_lshl_add_u64 v[122:123], v[122:123], 0, s[20:21]
	global_load_dwordx4 v[176:179], v[122:123], off
	global_load_dwordx4 v[180:183], v[122:123], off offset:1024
	global_load_dwordx4 v[184:187], v[122:123], off offset:2048
	global_load_dwordx4 v[188:191], v[122:123], off offset:3072
	v_lshl_add_u64 v[122:123], v[122:123], 0, s[20:21]
	global_load_dwordx4 v[192:195], v[122:123], off
	global_load_dwordx4 v[196:199], v[122:123], off offset:1024
	global_load_dwordx4 v[200:203], v[122:123], off offset:2048
	global_load_dwordx4 v[204:207], v[122:123], off offset:3072
	s_waitcnt vmcnt(0)
	v_pk_add_f32 v[88:89], v[88:89], v[104:105]
	v_pk_add_f32 v[90:91], v[90:91], v[106:107]
	v_pk_add_f32 v[88:89], v[88:89], v[160:161]
	v_pk_add_f32 v[90:91], v[90:91], v[162:163]
	v_pk_add_f32 v[88:89], v[88:89], v[176:177]
	v_pk_add_f32 v[90:91], v[90:91], v[178:179]
	v_pk_add_f32 v[88:89], v[88:89], v[192:193]
	v_pk_add_f32 v[90:91], v[90:91], v[194:195]
	v_pk_add_f32 v[92:93], v[92:93], v[108:109]
	v_pk_add_f32 v[94:95], v[94:95], v[110:111]
	v_pk_add_f32 v[92:93], v[92:93], v[164:165]
	v_pk_add_f32 v[94:95], v[94:95], v[166:167]
	v_pk_add_f32 v[92:93], v[92:93], v[180:181]
	v_pk_add_f32 v[94:95], v[94:95], v[182:183]
	v_pk_add_f32 v[92:93], v[92:93], v[196:197]
	v_pk_add_f32 v[94:95], v[94:95], v[198:199]
	v_pk_add_f32 v[96:97], v[96:97], v[112:113]
	v_pk_add_f32 v[98:99], v[98:99], v[114:115]
	v_pk_add_f32 v[96:97], v[96:97], v[168:169]
	v_pk_add_f32 v[98:99], v[98:99], v[170:171]
	v_pk_add_f32 v[96:97], v[96:97], v[184:185]
	v_pk_add_f32 v[98:99], v[98:99], v[186:187]
	v_pk_add_f32 v[96:97], v[96:97], v[200:201]
	v_pk_add_f32 v[98:99], v[98:99], v[202:203]
	v_pk_add_f32 v[100:101], v[100:101], v[116:117]
	v_pk_add_f32 v[102:103], v[102:103], v[118:119]
	v_pk_add_f32 v[100:101], v[100:101], v[172:173]
	v_pk_add_f32 v[102:103], v[102:103], v[174:175]
	v_pk_add_f32 v[100:101], v[100:101], v[188:189]
	v_pk_add_f32 v[102:103], v[102:103], v[190:191]
	v_pk_add_f32 v[100:101], v[100:101], v[204:205]
	v_pk_add_f32 v[102:103], v[102:103], v[206:207]
	v_mul_f32_e32 v124, v92, v92
	v_mul_f32_e32 v125, v88, v88
	v_mul_f32_e32 v126, v100, v100
	v_mul_f32_e32 v127, v96, v96
	v_fmac_f32_e32 v124, v93, v93
	v_fmac_f32_e32 v125, v89, v89
	v_fmac_f32_e32 v126, v101, v101
	v_fmac_f32_e32 v127, v97, v97
	v_fmac_f32_e32 v124, v94, v94
	v_fmac_f32_e32 v125, v90, v90
	v_fmac_f32_e32 v126, v102, v102
	v_fmac_f32_e32 v127, v98, v98
	v_fmac_f32_e32 v124, v95, v95
	v_fmac_f32_e32 v125, v91, v91
	v_fmac_f32_e32 v126, v103, v103
	v_fmac_f32_e32 v127, v99, v99
	v_add_f32_e32 v128, v124, v125
	v_add_f32_e32 v128, v127, v128
	v_add_f32_e32 v128, v126, v128
	ds_bpermute_b32 v129, v1, v128
	s_waitcnt lgkmcnt(0)
	v_add_f32_e32 v128, v128, v129
	ds_bpermute_b32 v129, v40, v128
	s_waitcnt lgkmcnt(0)
	v_add_f32_e32 v128, v128, v129
	ds_bpermute_b32 v129, v41, v128
	s_waitcnt lgkmcnt(0)
	v_add_f32_e32 v128, v128, v129
	ds_bpermute_b32 v129, v42, v128
	s_waitcnt lgkmcnt(0)
	v_add_f32_e32 v128, v128, v129
	ds_bpermute_b32 v129, v43, v128
	s_waitcnt lgkmcnt(0)
	v_add_f32_e32 v128, v128, v129
	ds_bpermute_b32 v129, v44, v128
	s_waitcnt lgkmcnt(0)
	v_add_f32_e32 v128, v128, v129
	v_fmamk_f32 v128, v128, 0x3a800000, v211
	v_cmp_gt_f32_e32 vcc, s26, v128
	v_mul_f32_e32 v129, 0x4b800000, v128
	s_nop 0
	v_cndmask_b32_e32 v128, v128, v129, vcc
	v_rsq_f32_e32 v128, v128
	s_nop 0
	v_mul_f32_e32 v129, 0x45800000, v128
	v_cndmask_b32_e32 v140, v128, v129, vcc
	s_nop 0
	v_pk_mul_f32 v[142:143], v[72:73], v[140:141] op_sel_hi:[1,0]
	v_pk_mul_f32 v[144:145], v[74:75], v[140:141] op_sel_hi:[1,0]
	v_pk_mul_f32 v[146:147], v[76:77], v[140:141] op_sel_hi:[1,0]
	v_pk_mul_f32 v[148:149], v[78:79], v[140:141] op_sel_hi:[1,0]
	v_pk_mul_f32 v[150:151], v[80:81], v[140:141] op_sel_hi:[1,0]
	v_pk_mul_f32 v[152:153], v[82:83], v[140:141] op_sel_hi:[1,0]
	v_pk_mul_f32 v[154:155], v[84:85], v[140:141] op_sel_hi:[1,0]
	v_pk_mul_f32 v[156:157], v[86:87], v[140:141] op_sel_hi:[1,0]
	v_pk_mul_f32 v[88:89], v[88:89], v[142:143]
	v_pk_mul_f32 v[90:91], v[90:91], v[144:145]
	v_pk_mul_f32 v[92:93], v[92:93], v[146:147]
	v_pk_mul_f32 v[94:95], v[94:95], v[148:149]
	v_pk_mul_f32 v[96:97], v[96:97], v[150:151]
	v_pk_mul_f32 v[98:99], v[98:99], v[152:153]
	v_pk_mul_f32 v[100:101], v[100:101], v[154:155]
	v_pk_mul_f32 v[102:103], v[102:103], v[156:157]
	global_store_dwordx4 v[120:121], v[88:91], off
	global_store_dwordx4 v[120:121], v[92:95], off offset:1024
	global_store_dwordx4 v[120:121], v[96:99], off offset:2048
	global_store_dwordx4 v[120:121], v[100:103], off offset:3072
	s_branch .LBB0_605
	s_branch .LBB0_603

.LBB0_633:
	s_andn2_b64 vcc, exec, s[6:7]
	s_cbranch_vccnz .LBB0_635
	s_cmp_lg_u32 s25, 0x100
	s_cbranch_scc1 .Lp0d_orig
	s_load_dwordx2 s[10:11], s[0:1], 0xb0
	v_and_b32_e32 v72, 63, v208
	v_lshrrev_b32_e32 v73, 6, v208
	v_mul_u32_u24_e32 v82, 65, v73
	v_add_lshl_u32 v82, v82, v72, 2
	v_lshrrev_b32_e32 v83, 3, v208
	v_and_b32_e32 v84, 7, v208
	v_lshlrev_b32_e32 v84, 3, v84
	v_mul_u32_u24_e32 v85, 0x104, v84
	v_lshl_add_u32 v85, v83, 2, v85
	v_add_u32_e32 v87, 0x4200, v82
	v_add_u32_e32 v88, 0x4200, v85
	v_add_u32_e32 v89, 0x410, v85
	v_add_u32_e32 v90, 0x410, v88
	v_lshlrev_b32_e32 v91, 11, v83
	v_lshl_add_u32 v91, v84, 1, v91
	v_lshlrev_b32_e32 v94, 12, v73
	v_lshl_add_u32 v94, v72, 2, v94
	v_add_u32_e32 v173, 0x8000, v94
	v_add_u32_e32 v174, 0x10000, v94
	v_add_u32_e32 v175, 0x18000, v94
	v_add_u32_e32 v176, 0x20000, v94
	v_add_u32_e32 v177, 0x28000, v94
	v_add_u32_e32 v178, 0x30000, v94
	v_add_u32_e32 v179, 0x38000, v94
	v_lshlrev_b32_e32 v93, 13, v83
	v_lshl_add_u32 v93, v84, 1, v93
	s_waitcnt lgkmcnt(0)
	s_mov_b32 s34, s52
	s_add_i32 s30, s34, 0xfffff1c0
	s_lshr_b32 s30, s30, 6
	s_and_b32 s6, s34, 63
	s_lshl_b32 s6, s6, 18
	s_lshl_b32 s30, s30, 8
	s_add_u32 s6, s6, s30
	s_add_u32 s12, s10, s6
	s_addc_u32 s13, s11, 0
	global_load_dword v108, v94, s[12:13]
	global_load_dword v109, v173, s[12:13]
	global_load_dword v110, v174, s[12:13]
	global_load_dword v111, v175, s[12:13]
	global_load_dword v112, v176, s[12:13]
	global_load_dword v113, v177, s[12:13]
	global_load_dword v114, v178, s[12:13]
	global_load_dword v115, v179, s[12:13]
	s_add_i32 s34, s34, s25
	s_add_i32 s30, s34, 0xfffff1c0
	s_lshr_b32 s30, s30, 6
	s_and_b32 s6, s34, 63
	s_lshl_b32 s6, s6, 18
	s_lshl_b32 s30, s30, 8
	s_add_u32 s6, s6, s30
	s_add_u32 s12, s10, s6
	s_addc_u32 s13, s11, 0
	global_load_dword v116, v94, s[12:13]
	global_load_dword v117, v173, s[12:13]
	global_load_dword v118, v174, s[12:13]
	global_load_dword v119, v175, s[12:13]
	global_load_dword v120, v176, s[12:13]
	global_load_dword v121, v177, s[12:13]
	global_load_dword v122, v178, s[12:13]
	global_load_dword v123, v179, s[12:13]
	s_add_i32 s34, s34, s25
	s_add_i32 s30, s34, 0xfffff1c0
	s_lshr_b32 s30, s30, 6
	s_and_b32 s6, s34, 63
	s_lshl_b32 s6, s6, 18
	s_lshl_b32 s30, s30, 8
	s_add_u32 s6, s6, s30
	s_add_u32 s12, s10, s6
	s_addc_u32 s13, s11, 0
	global_load_dword v124, v94, s[12:13]
	global_load_dword v125, v173, s[12:13]
	global_load_dword v126, v174, s[12:13]
	global_load_dword v127, v175, s[12:13]
	global_load_dword v128, v176, s[12:13]
	global_load_dword v129, v177, s[12:13]
	global_load_dword v130, v178, s[12:13]
	global_load_dword v131, v179, s[12:13]
	s_add_i32 s34, s34, s25
	s_add_i32 s30, s34, 0xfffff1c0
	s_lshr_b32 s30, s30, 6
	s_and_b32 s6, s34, 63
	s_lshl_b32 s6, s6, 18
	s_lshl_b32 s30, s30, 8
	s_add_u32 s6, s6, s30
	s_add_u32 s12, s10, s6
	s_addc_u32 s13, s11, 0
	global_load_dword v132, v94, s[12:13]
	global_load_dword v133, v173, s[12:13]
	global_load_dword v134, v174, s[12:13]
	global_load_dword v135, v175, s[12:13]
	global_load_dword v136, v176, s[12:13]
	global_load_dword v137, v177, s[12:13]
	global_load_dword v138, v178, s[12:13]
	global_load_dword v139, v179, s[12:13]
	s_add_i32 s34, s34, s25
	s_waitcnt vmcnt(24)
	s_add_i32 s30, s52, 0xfffff1c0
	s_lshr_b32 s30, s30, 6
	s_lshl_b32 s30, s30, 19
	s_and_b32 s6, s52, 63
	s_lshl_b32 s6, s6, 7
	s_add_u32 s30, s30, s6
	s_add_u32 s12, s20, s30
	s_addc_u32 s13, s21, 0
	ds_write_b32 v82, v108
	ds_write_b32 v82, v109 offset:2080
	ds_write_b32 v82, v110 offset:4160
	ds_write_b32 v82, v111 offset:6240
	ds_write_b32 v82, v112 offset:8320
	ds_write_b32 v82, v113 offset:10400
	ds_write_b32 v82, v114 offset:12480
	ds_write_b32 v82, v115 offset:14560
	s_waitcnt lgkmcnt(0)
	s_barrier
	ds_read2_b32 v[96:97], v85 offset1:65
	ds_read2_b32 v[98:99], v85 offset0:130 offset1:195
	ds_read2_b32 v[100:101], v89 offset1:65
	ds_read2_b32 v[102:103], v89 offset0:130 offset1:195
	s_waitcnt lgkmcnt(0)
	v_cvt_pk_bf16_f32 v104, v96, v97
	v_cvt_pk_bf16_f32 v105, v98, v99
	v_cvt_pk_bf16_f32 v106, v100, v101
	v_cvt_pk_bf16_f32 v107, v102, v103
	global_store_dwordx4 v93, v[104:107], s[12:13]
	s_add_i32 s52, s52, s25
	s_waitcnt vmcnt(17)
	s_add_i32 s30, s52, 0xfffff1c0
	s_lshr_b32 s30, s30, 6
	s_lshl_b32 s30, s30, 19
	s_and_b32 s6, s52, 63
	s_lshl_b32 s6, s6, 7
	s_add_u32 s30, s30, s6
	s_add_u32 s12, s20, s30
	s_addc_u32 s13, s21, 0
	ds_write_b32 v87, v116
	ds_write_b32 v87, v117 offset:2080
	ds_write_b32 v87, v118 offset:4160
	ds_write_b32 v87, v119 offset:6240
	ds_write_b32 v87, v120 offset:8320
	ds_write_b32 v87, v121 offset:10400
	ds_write_b32 v87, v122 offset:12480
	ds_write_b32 v87, v123 offset:14560
	s_waitcnt lgkmcnt(0)
	s_barrier
	ds_read2_b32 v[96:97], v88 offset1:65
	ds_read2_b32 v[98:99], v88 offset0:130 offset1:195
	ds_read2_b32 v[100:101], v90 offset1:65
	ds_read2_b32 v[102:103], v90 offset0:130 offset1:195
	s_waitcnt lgkmcnt(0)
	v_cvt_pk_bf16_f32 v104, v96, v97
	v_cvt_pk_bf16_f32 v105, v98, v99
	v_cvt_pk_bf16_f32 v106, v100, v101
	v_cvt_pk_bf16_f32 v107, v102, v103
	global_store_dwordx4 v93, v[104:107], s[12:13]
	s_add_i32 s52, s52, s25
	s_waitcnt vmcnt(10)
	s_add_i32 s30, s52, 0xfffff1c0
	s_lshr_b32 s30, s30, 6
	s_lshl_b32 s30, s30, 19
	s_and_b32 s6, s52, 63
	s_lshl_b32 s6, s6, 7
	s_add_u32 s30, s30, s6
	s_add_u32 s12, s20, s30
	s_addc_u32 s13, s21, 0
	ds_write_b32 v82, v124
	ds_write_b32 v82, v125 offset:2080
	ds_write_b32 v82, v126 offset:4160
	ds_write_b32 v82, v127 offset:6240
	ds_write_b32 v82, v128 offset:8320
	ds_write_b32 v82, v129 offset:10400
	ds_write_b32 v82, v130 offset:12480
	ds_write_b32 v82, v131 offset:14560
	s_waitcnt lgkmcnt(0)
	s_barrier
	ds_read2_b32 v[96:97], v85 offset1:65
	ds_read2_b32 v[98:99], v85 offset0:130 offset1:195
	ds_read2_b32 v[100:101], v89 offset1:65
	ds_read2_b32 v[102:103], v89 offset0:130 offset1:195
	s_waitcnt lgkmcnt(0)
	v_cvt_pk_bf16_f32 v104, v96, v97
	v_cvt_pk_bf16_f32 v105, v98, v99
	v_cvt_pk_bf16_f32 v106, v100, v101
	v_cvt_pk_bf16_f32 v107, v102, v103
	global_store_dwordx4 v93, v[104:107], s[12:13]
	s_add_i32 s52, s52, s25
	s_waitcnt vmcnt(3)
	s_add_i32 s30, s52, 0xfffff1c0
	s_lshr_b32 s30, s30, 6
	s_lshl_b32 s30, s30, 19
	s_and_b32 s6, s52, 63
	s_lshl_b32 s6, s6, 7
	s_add_u32 s30, s30, s6
	s_add_u32 s12, s20, s30
	s_addc_u32 s13, s21, 0
	ds_write_b32 v87, v132
	ds_write_b32 v87, v133 offset:2080
	ds_write_b32 v87, v134 offset:4160
	ds_write_b32 v87, v135 offset:6240
	ds_write_b32 v87, v136 offset:8320
	ds_write_b32 v87, v137 offset:10400
	ds_write_b32 v87, v138 offset:12480
	ds_write_b32 v87, v139 offset:14560
	s_waitcnt lgkmcnt(0)
	s_barrier
	ds_read2_b32 v[96:97], v88 offset1:65
	ds_read2_b32 v[98:99], v88 offset0:130 offset1:195
	ds_read2_b32 v[100:101], v90 offset1:65
	ds_read2_b32 v[102:103], v90 offset0:130 offset1:195
	s_waitcnt lgkmcnt(0)
	v_cvt_pk_bf16_f32 v104, v96, v97
	v_cvt_pk_bf16_f32 v105, v98, v99
	v_cvt_pk_bf16_f32 v106, v100, v101
	v_cvt_pk_bf16_f32 v107, v102, v103
	global_store_dwordx4 v93, v[104:107], s[12:13]
	s_add_i32 s52, s52, s25
	s_barrier
	s_lshl_b32 s68, s52, 6
	s_branch .LBB0_628
.Lp0d_orig:
	s_load_dwordx2 s[6:7], s[0:1], 0xb0
	s_and_b32 s10, s52, 0x1fc0
	s_and_b32 s11, s52, 63
	s_add_i32 s30, s10, 0xfffff1c0
	s_lshl_b32 s10, s11, 18
	v_mov_b32_e32 v1, v208
	s_waitcnt lgkmcnt(0)
	s_add_u32 s6, s6, s10
	s_addc_u32 s7, s7, 0
	s_waitcnt vmcnt(0)
	v_ashrrev_i32_e32 v6, 6, v1
	v_or_b32_e32 v4, s30, v2
	v_mov_b32_e32 v5, v0
	v_ashrrev_i32_e32 v7, 31, v6
	v_lshl_add_u64 v[4:5], v[4:5], 2, s[6:7]
	v_lshlrev_b64 v[8:9], 12, v[6:7]
	v_lshl_add_u64 v[4:5], v[4:5], 0, v[8:9]
	s_mov_b32 s6, 0x8000
	v_add_co_u32_e32 v8, vcc, s6, v4
	s_mov_b32 s6, 0x18000
	s_nop 0
	v_addc_co_u32_e32 v9, vcc, 0, v5, vcc
	v_add_co_u32_e32 v10, vcc, s73, v4
	v_mul_lo_u32 v6, v6, s95
	s_nop 0
	v_addc_co_u32_e32 v11, vcc, 0, v5, vcc
	v_add_co_u32_e32 v12, vcc, s6, v4
	s_mov_b32 s6, 0x28000
	s_nop 0
	v_addc_co_u32_e32 v13, vcc, 0, v5, vcc
	v_add_co_u32_e32 v14, vcc, s19, v4
	s_nop 1
	v_addc_co_u32_e32 v15, vcc, 0, v5, vcc
	v_add_co_u32_e32 v16, vcc, s6, v4
	s_mov_b32 s6, 0x30000
	s_nop 0
	v_addc_co_u32_e32 v17, vcc, 0, v5, vcc
	v_add_co_u32_e32 v18, vcc, s6, v4
	s_mov_b32 s6, 0x38000
	s_nop 0
	v_addc_co_u32_e32 v19, vcc, 0, v5, vcc
	v_add_co_u32_e32 v20, vcc, s6, v4
	s_lshl_b64 s[6:7], s[30:31], 13
	s_nop 0
	v_addc_co_u32_e32 v21, vcc, 0, v5, vcc
	global_load_dword v3, v[4:5], off
	global_load_dword v22, v[8:9], off
	s_nop 0
	global_load_dword v10, v[10:11], off
	s_nop 0
	global_load_dword v11, v[12:13], off
	s_nop 0
	global_load_dword v12, v[14:15], off
	global_load_dword v13, v[16:17], off
	s_nop 0
	global_load_dword v14, v[18:19], off
	global_load_dword v15, v[20:21], off
	v_and_b32_e32 v4, 63, v1
	v_ashrrev_i32_e32 v8, 3, v1
	v_lshlrev_b32_e32 v1, 3, v1
	v_and_b32_e32 v1, 56, v1
	v_lshlrev_b32_e32 v4, 2, v4
	v_lshlrev_b32_e32 v16, 2, v8
	v_mul_u32_u24_e32 v18, 0x104, v1
	v_ashrrev_i32_e32 v9, 31, v8
	v_add3_u32 v17, 0, v4, v6
	v_lshlrev_b32_e32 v4, 1, v1
	v_add3_u32 v1, 0, v18, v16
	s_add_u32 s6, s20, s6
	v_lshlrev_b64 v[6:7], 13, v[8:9]
	v_add_u32_e32 v16, 0x400, v1
	s_addc_u32 s7, s21, s7
	s_lshl_b32 s10, s11, 7
	s_add_u32 s6, s6, s10
	s_addc_u32 s7, s7, 0
	v_mov_b32_e32 v5, v0
	v_lshl_add_u64 v[6:7], s[6:7], 0, v[6:7]
	s_waitcnt vmcnt(7)
	ds_write_b32 v17, v3
	s_waitcnt vmcnt(6)
	ds_write_b32 v17, v22 offset:2080
	s_waitcnt vmcnt(5)
	ds_write_b32 v17, v10 offset:4160
	s_waitcnt vmcnt(4)
	ds_write_b32 v17, v11 offset:6240
	s_waitcnt vmcnt(3)
	ds_write_b32 v17, v12 offset:8320
	s_waitcnt vmcnt(2)
	ds_write_b32 v17, v13 offset:10400
	s_waitcnt vmcnt(1)
	ds_write_b32 v17, v14 offset:12480
	s_waitcnt vmcnt(0)
	ds_write_b32 v17, v15 offset:14560
	s_waitcnt lgkmcnt(0)
	s_barrier
	ds_read2_b32 v[8:9], v1 offset1:65
	ds_read2_b32 v[10:11], v1 offset0:130 offset1:195
	ds_read2_b32 v[12:13], v16 offset0:4 offset1:69
	ds_read2_b32 v[14:15], v16 offset0:134 offset1:199
	v_lshl_add_u64 v[16:17], v[6:7], 0, v[4:5]
	s_waitcnt lgkmcnt(3)
	v_cvt_pk_bf16_f32 v4, v8, v9
	s_waitcnt lgkmcnt(2)
	v_cvt_pk_bf16_f32 v5, v10, v11
	s_waitcnt lgkmcnt(1)
	v_cvt_pk_bf16_f32 v6, v12, v13
	s_waitcnt lgkmcnt(0)
	v_cvt_pk_bf16_f32 v7, v14, v15
	global_store_dwordx4 v[16:17], v[4:7], off
	s_barrier

.LBB0_655:
	s_andn2_b64 vcc, exec, s[6:7]
	s_cbranch_vccnz .LBB0_657
	s_cmp_lg_u32 s25, 0x100
	s_cbranch_scc1 .Lp0p_orig
	v_and_b32_e32 v72, 63, v208
	v_lshrrev_b32_e32 v73, 6, v208
	v_mul_u32_u24_e32 v82, 65, v73
	v_add_lshl_u32 v82, v82, v72, 2
	v_lshrrev_b32_e32 v83, 3, v208
	v_and_b32_e32 v84, 7, v208
	v_lshlrev_b32_e32 v84, 3, v84
	v_mul_u32_u24_e32 v85, 0x104, v84
	v_lshl_add_u32 v85, v83, 2, v85
	v_add_u32_e32 v87, 0x4200, v82
	v_add_u32_e32 v88, 0x4200, v85
	v_add_u32_e32 v89, 0x410, v85
	v_add_u32_e32 v90, 0x410, v88
	v_lshlrev_b32_e32 v91, 11, v83
	v_lshl_add_u32 v91, v84, 1, v91
	v_lshlrev_b32_e32 v94, 12, v73
	v_lshl_add_u32 v94, v72, 2, v94
	v_add_u32_e32 v173, 0x8000, v94
	v_add_u32_e32 v174, 0x10000, v94
	v_add_u32_e32 v175, 0x18000, v94
	v_add_u32_e32 v176, 0x20000, v94
	v_add_u32_e32 v177, 0x28000, v94
	v_add_u32_e32 v178, 0x30000, v94
	v_add_u32_e32 v179, 0x38000, v94
	s_mov_b32 s34, s52
	s_add_i32 s30, s34, 0xfffff8c0
	s_lshr_b32 s7, s30, 8
	s_lshl_b32 s77, s7, 3
	s_load_dwordx2 s[10:11], s[0:1], s77 offset:0x88
	s_bfe_u32 s76, s30, 0x40004
	s_and_b32 s6, s34, 15
	s_lshl_b32 s6, s6, 18
	s_lshl_b32 s76, s76, 8
	s_add_u32 s6, s6, s76
	s_waitcnt lgkmcnt(0)
	s_add_u32 s12, s10, s6
	s_addc_u32 s13, s11, 0
	global_load_dword v108, v94, s[12:13]
	global_load_dword v109, v173, s[12:13]
	global_load_dword v110, v174, s[12:13]
	global_load_dword v111, v175, s[12:13]
	global_load_dword v112, v176, s[12:13]
	global_load_dword v113, v177, s[12:13]
	global_load_dword v114, v178, s[12:13]
	global_load_dword v115, v179, s[12:13]
	s_add_i32 s34, s34, s25
	s_add_i32 s30, s34, 0xfffff8c0
	s_lshr_b32 s7, s30, 8
	s_lshl_b32 s77, s7, 3
	s_load_dwordx2 s[10:11], s[0:1], s77 offset:0x88
	s_bfe_u32 s76, s30, 0x40004
	s_and_b32 s6, s34, 15
	s_lshl_b32 s6, s6, 18
	s_lshl_b32 s76, s76, 8
	s_add_u32 s6, s6, s76
	s_waitcnt lgkmcnt(0)
	s_add_u32 s12, s10, s6
	s_addc_u32 s13, s11, 0
	global_load_dword v116, v94, s[12:13]
	global_load_dword v117, v173, s[12:13]
	global_load_dword v118, v174, s[12:13]
	global_load_dword v119, v175, s[12:13]
	global_load_dword v120, v176, s[12:13]
	global_load_dword v121, v177, s[12:13]
	global_load_dword v122, v178, s[12:13]
	global_load_dword v123, v179, s[12:13]
	s_add_i32 s34, s34, s25
	s_add_i32 s30, s34, 0xfffff8c0
	s_lshr_b32 s7, s30, 8
	s_lshl_b32 s77, s7, 3
	s_load_dwordx2 s[10:11], s[0:1], s77 offset:0x88
	s_bfe_u32 s76, s30, 0x40004
	s_and_b32 s6, s34, 15
	s_lshl_b32 s6, s6, 18
	s_lshl_b32 s76, s76, 8
	s_add_u32 s6, s6, s76
	s_waitcnt lgkmcnt(0)
	s_add_u32 s12, s10, s6
	s_addc_u32 s13, s11, 0
	global_load_dword v124, v94, s[12:13]
	global_load_dword v125, v173, s[12:13]
	global_load_dword v126, v174, s[12:13]
	global_load_dword v127, v175, s[12:13]
	global_load_dword v128, v176, s[12:13]
	global_load_dword v129, v177, s[12:13]
	global_load_dword v130, v178, s[12:13]
	global_load_dword v131, v179, s[12:13]
	s_add_i32 s34, s34, s25
	s_waitcnt vmcnt(16)
	s_add_i32 s30, s52, 0xfffff8c0
	s_lshr_b32 s7, s30, 8
	s_lshl_b32 s7, s7, 21
	s_bfe_u32 s76, s30, 0x40004
	s_lshl_b32 s76, s76, 17
	s_add_u32 s7, s7, s76
	s_and_b32 s6, s52, 15
	s_lshl_b32 s6, s6, 7
	s_add_u32 s7, s7, s6
	s_add_u32 s12, s56, s7
	s_addc_u32 s13, s65, 0
	ds_write_b32 v82, v108
	ds_write_b32 v82, v109 offset:2080
	ds_write_b32 v82, v110 offset:4160
	ds_write_b32 v82, v111 offset:6240
	ds_write_b32 v82, v112 offset:8320
	ds_write_b32 v82, v113 offset:10400
	ds_write_b32 v82, v114 offset:12480
	ds_write_b32 v82, v115 offset:14560
	s_waitcnt lgkmcnt(0)
	s_barrier
	ds_read2_b32 v[96:97], v85 offset1:65
	ds_read2_b32 v[98:99], v85 offset0:130 offset1:195
	ds_read2_b32 v[100:101], v89 offset1:65
	ds_read2_b32 v[102:103], v89 offset0:130 offset1:195
	s_waitcnt lgkmcnt(0)
	v_cvt_pk_bf16_f32 v104, v96, v97
	v_cvt_pk_bf16_f32 v105, v98, v99
	v_cvt_pk_bf16_f32 v106, v100, v101
	v_cvt_pk_bf16_f32 v107, v102, v103
	global_store_dwordx4 v91, v[104:107], s[12:13]
	s_add_i32 s52, s52, s25
	s_waitcnt vmcnt(9)
	s_add_i32 s30, s52, 0xfffff8c0
	s_lshr_b32 s7, s30, 8
	s_lshl_b32 s7, s7, 21
	s_bfe_u32 s76, s30, 0x40004
	s_lshl_b32 s76, s76, 17
	s_add_u32 s7, s7, s76
	s_and_b32 s6, s52, 15
	s_lshl_b32 s6, s6, 7
	s_add_u32 s7, s7, s6
	s_add_u32 s12, s56, s7
	s_addc_u32 s13, s65, 0
	ds_write_b32 v87, v116
	ds_write_b32 v87, v117 offset:2080
	ds_write_b32 v87, v118 offset:4160
	ds_write_b32 v87, v119 offset:6240
	ds_write_b32 v87, v120 offset:8320
	ds_write_b32 v87, v121 offset:10400
	ds_write_b32 v87, v122 offset:12480
	ds_write_b32 v87, v123 offset:14560
	s_waitcnt lgkmcnt(0)
	s_barrier
	ds_read2_b32 v[96:97], v88 offset1:65
	ds_read2_b32 v[98:99], v88 offset0:130 offset1:195
	ds_read2_b32 v[100:101], v90 offset1:65
	ds_read2_b32 v[102:103], v90 offset0:130 offset1:195
	s_waitcnt lgkmcnt(0)
	v_cvt_pk_bf16_f32 v104, v96, v97
	v_cvt_pk_bf16_f32 v105, v98, v99
	v_cvt_pk_bf16_f32 v106, v100, v101
	v_cvt_pk_bf16_f32 v107, v102, v103
	global_store_dwordx4 v91, v[104:107], s[12:13]
	s_add_i32 s52, s52, s25
	s_waitcnt vmcnt(2)
	s_add_i32 s30, s52, 0xfffff8c0
	s_lshr_b32 s7, s30, 8
	s_lshl_b32 s7, s7, 21
	s_bfe_u32 s76, s30, 0x40004
	s_lshl_b32 s76, s76, 17
	s_add_u32 s7, s7, s76
	s_and_b32 s6, s52, 15
	s_lshl_b32 s6, s6, 7
	s_add_u32 s7, s7, s6
	s_add_u32 s12, s56, s7
	s_addc_u32 s13, s65, 0
	ds_write_b32 v82, v124
	ds_write_b32 v82, v125 offset:2080
	ds_write_b32 v82, v126 offset:4160
	ds_write_b32 v82, v127 offset:6240
	ds_write_b32 v82, v128 offset:8320
	ds_write_b32 v82, v129 offset:10400
	ds_write_b32 v82, v130 offset:12480
	ds_write_b32 v82, v131 offset:14560
	s_waitcnt lgkmcnt(0)
	s_barrier
	ds_read2_b32 v[96:97], v85 offset1:65
	ds_read2_b32 v[98:99], v85 offset0:130 offset1:195
	ds_read2_b32 v[100:101], v89 offset1:65
	ds_read2_b32 v[102:103], v89 offset0:130 offset1:195
	s_waitcnt lgkmcnt(0)
	v_cvt_pk_bf16_f32 v104, v96, v97
	v_cvt_pk_bf16_f32 v105, v98, v99
	v_cvt_pk_bf16_f32 v106, v100, v101
	v_cvt_pk_bf16_f32 v107, v102, v103
	global_store_dwordx4 v91, v[104:107], s[12:13]
	s_add_i32 s52, s52, s25
	s_barrier
	s_lshl_b32 s68, s52, 6
	s_branch .LBB0_628
.Lp0p_orig:
	s_add_i32 s6, s52, 0xfffff8c0
	s_lshr_b32 s30, s6, 8
	s_bfe_u32 s12, s6, 0x40004
	s_lshl_b32 s6, s30, 3
	s_load_dwordx2 s[6:7], s[0:1], s6 offset:0x88
	s_and_b32 s13, s52, 15
	s_lshl_b64 s[10:11], s[30:31], 21
	s_add_u32 s10, s56, s10
	s_addc_u32 s11, s65, s11
	s_lshl_b32 s30, s13, 18
	v_mov_b32_e32 v1, v208
	s_waitcnt lgkmcnt(0)
	s_add_u32 s6, s6, s30
	v_lshlrev_b32_e32 v3, 2, v2
	v_ashrrev_i32_e32 v4, 6, v1
	s_addc_u32 s7, s7, 0
	s_waitcnt vmcnt(0)
	v_lshl_or_b32 v6, s12, 8, v3
	v_mov_b32_e32 v7, v0
	v_ashrrev_i32_e32 v5, 31, v4
	v_lshl_add_u64 v[6:7], s[6:7], 0, v[6:7]
	v_lshlrev_b64 v[8:9], 12, v[4:5]
	v_lshl_add_u64 v[6:7], v[6:7], 0, v[8:9]
	s_mov_b32 s6, 0x8000
	v_add_co_u32_e32 v8, vcc, s6, v6
	s_mov_b32 s6, 0x18000
	s_nop 0
	v_addc_co_u32_e32 v9, vcc, 0, v7, vcc
	v_add_co_u32_e32 v10, vcc, s73, v6
	v_mul_lo_u32 v4, v4, s95
	s_nop 0
	v_addc_co_u32_e32 v11, vcc, 0, v7, vcc
	v_add_co_u32_e32 v12, vcc, s6, v6
	s_mov_b32 s6, 0x28000
	s_nop 0
	v_addc_co_u32_e32 v13, vcc, 0, v7, vcc
	v_add_co_u32_e32 v14, vcc, s19, v6
	v_mov_b32_e32 v5, v0
	s_nop 0
	v_addc_co_u32_e32 v15, vcc, 0, v7, vcc
	v_add_co_u32_e32 v16, vcc, s6, v6
	s_mov_b32 s6, 0x30000
	s_nop 0
	v_addc_co_u32_e32 v17, vcc, 0, v7, vcc
	v_add_co_u32_e32 v18, vcc, s6, v6
	s_mov_b32 s6, 0x38000
	s_nop 0
	v_addc_co_u32_e32 v19, vcc, 0, v7, vcc
	v_add_co_u32_e32 v20, vcc, s6, v6
	s_lshl_b32 s6, s12, 17
	s_nop 0
	v_addc_co_u32_e32 v21, vcc, 0, v7, vcc
	global_load_dword v3, v[6:7], off
	s_nop 0
	global_load_dword v8, v[8:9], off
	s_nop 0
	global_load_dword v9, v[10:11], off
	s_nop 0
	global_load_dword v10, v[12:13], off
	global_load_dword v11, v[14:15], off
	s_nop 0
	global_load_dword v12, v[16:17], off
	global_load_dword v13, v[18:19], off
	global_load_dword v14, v[20:21], off
	v_and_b32_e32 v7, 63, v1
	v_ashrrev_i32_e32 v6, 3, v1
	v_lshlrev_b32_e32 v1, 3, v1
	v_and_b32_e32 v1, 56, v1
	v_lshlrev_b32_e32 v15, 2, v7
	v_lshlrev_b32_e32 v16, 2, v6
	v_mul_u32_u24_e32 v17, 0x104, v1
	v_add3_u32 v15, 0, v15, v4
	v_lshlrev_b32_e32 v4, 1, v1
	v_add3_u32 v1, 0, v17, v16
	s_add_u32 s6, s10, s6
	v_add_u32_e32 v16, 0x400, v1
	s_addc_u32 s7, s11, 0
	s_lshl_b32 s10, s13, 7
	v_ashrrev_i32_e32 v7, 31, v6
	s_add_u32 s6, s6, s10
	v_lshlrev_b64 v[6:7], 11, v[6:7]
	s_addc_u32 s7, s7, 0
	v_lshl_add_u64 v[6:7], s[6:7], 0, v[6:7]
	s_waitcnt vmcnt(7)
	ds_write_b32 v15, v3
	s_waitcnt vmcnt(6)
	ds_write_b32 v15, v8 offset:2080
	s_waitcnt vmcnt(5)
	ds_write_b32 v15, v9 offset:4160
	s_waitcnt vmcnt(4)
	ds_write_b32 v15, v10 offset:6240
	s_waitcnt vmcnt(3)
	ds_write_b32 v15, v11 offset:8320
	s_waitcnt vmcnt(2)
	ds_write_b32 v15, v12 offset:10400
	s_waitcnt vmcnt(1)
	ds_write_b32 v15, v13 offset:12480
	s_waitcnt vmcnt(0)
	ds_write_b32 v15, v14 offset:14560
	s_waitcnt lgkmcnt(0)
	s_barrier
	ds_read2_b32 v[8:9], v1 offset1:65
	ds_read2_b32 v[10:11], v1 offset0:130 offset1:195
	ds_read2_b32 v[12:13], v16 offset0:4 offset1:69
	ds_read2_b32 v[14:15], v16 offset0:134 offset1:199
	v_lshl_add_u64 v[16:17], v[6:7], 0, v[4:5]
	s_waitcnt lgkmcnt(3)
	v_cvt_pk_bf16_f32 v4, v8, v9
	s_waitcnt lgkmcnt(2)
	v_cvt_pk_bf16_f32 v5, v10, v11
	s_waitcnt lgkmcnt(1)
	v_cvt_pk_bf16_f32 v6, v12, v13
	s_waitcnt lgkmcnt(0)
	v_cvt_pk_bf16_f32 v7, v14, v15
	global_store_dwordx4 v[16:17], v[4:7], off
	s_barrier
